# MLA steady-state steps lead with 12 softmax VALU ops before the first QK MFMA (was 3)
# baseline (speedup 1.0000x reference)
; template <bool MASK> __device__ __forceinline__ void sm_tile(f32x16& p0, f32x16& p1, float& mrun, float& lrun, f32x16& o0, f32x16& o1, LAS float* wsf, int kv0, int qpos, int q32, int hi) {
;     ...
;     float rm = fmaxf(p0[0], p1[0]);
; #pragma unroll
;     for (int r = 1; r < 16; ++r) rm = fmaxf(rm, fmaxf(p0[r], p1[r]));
;     rm = fmaxf(rm, xhalf(rm, hi));
;     if (__any(rm > mrun + 8.0f)) {
;         const float mnew = fmaxf(mrun, rm), alpha = ex2(mrun - mnew); mrun = mnew; lrun *= alpha;
;         if (hi == 0) wsf[q32] = alpha;
; template <bool MASK> __device__ __forceinline__ void sm_iter(int var, SmState& st, const bf16x8 (&qr)[6], const LAS unsigned char* kb, const LAS unsigned char* vb, LAS float* wsf, int kv0, int qpos, int q32, int hi) {
;     ...
;     for (int d0 = 0; d0 < ND; ++d0) { kf[2 * d0] = *(const LAS bf16x8*)(kb + d0 * 32); kf[2 * d0 + 1] = *(const LAS bf16x8*)(kb + 32 * KP + d0 * 32); }
;     __builtin_amdgcn_sched_barrier(0);
; #pragma unroll
;     for (int d0 = 0; d0 < ND; ++d0) { p0 = MFMA32(kf[2 * d0], qr[d0], p0); p1 = MFMA32(kf[2 * d0 + 1], qr[d0], p1); }
; #pragma unroll
;     for (int j = 0; j < 4; ++j) { vlo[2 * j] = *(const LAS s16x4*)(vb + j * 32); vhh[2 * j] = *(const LAS s16x4*)(vb + j * 32 + 16);
;         vlo[2 * j + 1] = *(const LAS s16x4*)(vb + 32 * VP + j * 32); vhh[2 * j + 1] = *(const LAS s16x4*)(vb + 32 * VP + j * 32 + 16); }
;     __builtin_amdgcn_sched_barrier(0);
;     if (var != 1) sm_tile<MASK>(p0, p1, st.mrun, st.lrun, st.o0, st.o1, wsf, kv0, qpos, q32, hi);
; #pragma unroll
;     for (int j = 0; j < 4; ++j) {
;         u32x4 pw;
;         if (j < 2) { const int r0 = 8 * (j & 1); pw.x = pk2(p0[r0], p0[r0 + 1]); pw.y = pk2(p0[r0 + 2], p0[r0 + 3]); pw.z = pk2(p0[r0 + 4], p0[r0 + 5]); pw.w = pk2(p0[r0 + 6], p0[r0 + 7]); }
;         else { const int r0 = 8 * (j & 1); pw.x = pk2(p1[r0], p1[r0 + 1]); pw.y = pk2(p1[r0 + 2], p1[r0 + 3]); pw.z = pk2(p1[r0 + 4], p1[r0 + 5]); pw.w = pk2(p1[r0 + 6], p1[r0 + 7]); }
;         const bf16x8 pa = __builtin_bit_cast(bf16x8, pw);
;         { const s16x4 lo = vlo[2 * j], hh = vhh[2 * j]; const bf16x8 vf = {lo[0], lo[1], lo[2], lo[3], hh[0], hh[1], hh[2], hh[3]}; st.o0 = MFMA32(pa, vf, st.o0); }
;         { const s16x4 lo = vlo[2 * j + 1], hh = vhh[2 * j + 1]; const bf16x8 vf = {lo[0], lo[1], lo[2], lo[3], hh[0], hh[1], hh[2], hh[3]}; st.o1 = MFMA32(pa, vf, st.o1); }
;     }
.Lm3_ok1:
.Lm3_body:
	v_exp_f32_e32 v64, v64
	v_exp_f32_e32 v65, v65
	v_exp_f32_e32 v66, v66
	v_add_f32_e32 v15, v64, v65
	v_exp_f32_e32 v67, v67
	v_cvt_pk_bf16_f32 v214, v64, v65
	v_exp_f32_e32 v68, v68
	v_add_f32_e32 v177, v66, v67
	v_exp_f32_e32 v69, v69
	v_cvt_pk_bf16_f32 v215, v66, v67
	v_exp_f32_e32 v70, v70
	v_add_f32_e32 v15, v15, v68
	s_waitcnt lgkmcnt(9)
	v_mfma_f32_32x32x16_bf16 v[48:63], v[116:119], v[84:87], v[198:213]
	v_exp_f32_e32 v71, v71
	v_add_f32_e32 v177, v177, v69
	v_exp_f32_e32 v72, v72
	v_cvt_pk_bf16_f32 v216, v68, v69
	v_exp_f32_e32 v73, v73
	s_waitcnt lgkmcnt(8)
	v_mfma_f32_32x32x16_bf16 v[48:63], v[120:123], v[88:91], v[48:63]
	v_add_f32_e32 v15, v15, v70
	v_exp_f32_e32 v74, v74
	v_add_f32_e32 v177, v177, v71
	v_exp_f32_e32 v75, v75
	v_cvt_pk_bf16_f32 v217, v70, v71
	s_waitcnt lgkmcnt(7)
	v_mfma_f32_32x32x16_bf16 v[48:63], v[124:127], v[92:95], v[48:63]
	v_exp_f32_e32 v76, v76
	v_add_f32_e32 v15, v15, v72
	v_exp_f32_e32 v77, v77
	v_add_f32_e32 v177, v177, v73
	v_exp_f32_e32 v78, v78
	s_waitcnt lgkmcnt(6)
	v_mfma_f32_32x32x16_bf16 v[48:63], v[128:131], v[96:99], v[48:63]
	v_cvt_pk_bf16_f32 v218, v72, v73
	v_exp_f32_e32 v79, v79
	v_add_f32_e32 v15, v15, v74
	v_add_f32_e32 v177, v177, v75
	v_cvt_pk_bf16_f32 v219, v74, v75
	s_waitcnt lgkmcnt(5)
	v_mfma_f32_32x32x16_bf16 v[48:63], v[132:135], v[100:103], v[48:63]
	v_add_f32_e32 v15, v15, v76
	v_add_f32_e32 v177, v177, v77
	v_cvt_pk_bf16_f32 v220, v76, v77
	v_add_f32_e32 v15, v15, v78
	s_waitcnt lgkmcnt(4)
	v_mfma_f32_32x32x16_bf16 v[48:63], v[136:139], v[104:107], v[48:63]
	v_add_f32_e32 v177, v177, v79
	v_cvt_pk_bf16_f32 v221, v78, v79
	v_add_f32_e32 v15, v15, v177
	v_add_f32_e32 v170, v170, v15
	s_waitcnt lgkmcnt(0)
	ds_read_b128 v[116:119], v1 offset:13312
	ds_read_b128 v[120:123], v1 offset:13344
	ds_read_b128 v[124:127], v1 offset:13376
	ds_read_b128 v[128:131], v1 offset:13408
	ds_read_b128 v[132:135], v1 offset:13440
	ds_read_b128 v[136:139], v1 offset:13472
	v_mfma_f32_32x32x16_bf16 v[16:31], v[214:217], v[140:143], v[16:31]
	ds_read2_b64 v[140:143], v14 offset0:8 offset1:10
	v_mfma_f32_32x32x16_bf16 v[32:47], v[214:217], v[144:147], v[32:47]
	ds_read2_b64 v[144:147], v176 offset0:40 offset1:42
	v_mfma_f32_32x32x16_bf16 v[16:31], v[218:221], v[180:183], v[16:31]
	ds_read2_b64 v[180:183], v14 offset0:12 offset1:14
	v_mfma_f32_32x32x16_bf16 v[32:47], v[218:221], v[184:187], v[32:47]
	ds_read2_b64 v[184:187], v176 offset0:44 offset1:46
	v_max3_f32 v15, v48, v49, v50
	v_max3_f32 v177, v51, v52, v53
	v_max3_f32 v15, v15, v54, v55
	v_max3_f32 v177, v177, v56, v57
	v_max3_f32 v15, v15, v58, v59
	v_max3_f32 v177, v177, v60, v61
	v_max3_f32 v15, v15, v62, v63
	v_max_f32_e32 v15, v15, v177
	v_mov_b32_e32 v177, v15
	v_mov_b32_e32 v178, v15
	s_nop 1
	v_permlane32_swap_b32_e32 v177, v178
	v_max3_f32 v15, v15, v177, v178
	v_cmp_gt_f32_e32 vcc, v15, v197
	s_cbranch_vccz .Lm3_ok2
	v_max_f32_e32 v15, v171, v15
	v_sub_f32_e32 v177, v171, v15
	v_exp_f32_e32 v177, v177
	v_sub_f32_e32 v198, v198, v15
	s_and_saveexec_b64 s[20:21], s[40:41]
	ds_write_b32 v149, v177
	s_or_b64 exec, exec, s[20:21]
	v_mul_f32_e32 v170, v170, v177
	v_add_u32_e32 v178, s25, v148
	s_waitcnt lgkmcnt(0)
	ds_read_b128 v[188:191], v178
	ds_read_b128 v[192:195], v178 offset:32
	ds_read_b128 v[222:225], v178 offset:64
	ds_read_b128 v[236:239], v178 offset:96
	v_sub_f32_e32 v48, v48, v15
	v_sub_f32_e32 v49, v49, v15
	v_sub_f32_e32 v50, v50, v15
	v_sub_f32_e32 v51, v51, v15
	v_sub_f32_e32 v52, v52, v15
	v_sub_f32_e32 v53, v53, v15
	v_sub_f32_e32 v54, v54, v15
	v_sub_f32_e32 v55, v55, v15
	v_sub_f32_e32 v56, v56, v15
	v_sub_f32_e32 v57, v57, v15
	v_sub_f32_e32 v58, v58, v15
	v_sub_f32_e32 v59, v59, v15
	v_sub_f32_e32 v60, v60, v15
	v_sub_f32_e32 v61, v61, v15
	v_sub_f32_e32 v62, v62, v15
	v_sub_f32_e32 v63, v63, v15
	v_mov_b32_e32 v199, v198
	v_mov_b32_e32 v200, v198
	v_mov_b32_e32 v201, v198
	v_mov_b32_e32 v202, v198
	v_mov_b32_e32 v203, v198
	v_mov_b32_e32 v204, v198
	v_mov_b32_e32 v205, v198
	v_mov_b32_e32 v206, v198
	v_mov_b32_e32 v207, v198
	v_mov_b32_e32 v208, v198
	v_mov_b32_e32 v209, v198
	v_mov_b32_e32 v210, v198
	v_mov_b32_e32 v211, v198
	v_mov_b32_e32 v212, v198
	v_mov_b32_e32 v213, v198
	v_mov_b32_e32 v171, 0
	v_mov_b32_e32 v197, 0x41000000
	s_nop 11
	s_nop 3
	s_waitcnt lgkmcnt(0)
	v_pk_mul_f32 v[16:17], v[16:17], v[188:189]
	v_pk_mul_f32 v[32:33], v[32:33], v[188:189]
	v_pk_mul_f32 v[18:19], v[18:19], v[190:191]
	v_pk_mul_f32 v[34:35], v[34:35], v[190:191]
	v_pk_mul_f32 v[20:21], v[20:21], v[192:193]
	v_pk_mul_f32 v[36:37], v[36:37], v[192:193]
	v_pk_mul_f32 v[22:23], v[22:23], v[194:195]
	v_pk_mul_f32 v[38:39], v[38:39], v[194:195]
	v_pk_mul_f32 v[24:25], v[24:25], v[222:223]
	v_pk_mul_f32 v[40:41], v[40:41], v[222:223]
	v_pk_mul_f32 v[26:27], v[26:27], v[224:225]
	v_pk_mul_f32 v[42:43], v[42:43], v[224:225]
	v_pk_mul_f32 v[28:29], v[28:29], v[236:237]
	v_pk_mul_f32 v[44:45], v[44:45], v[236:237]
	v_pk_mul_f32 v[30:31], v[30:31], v[238:239]
	v_pk_mul_f32 v[46:47], v[46:47], v[238:239]
; template <bool MASK> __device__ __forceinline__ void sm_tile(f32x16& p0, f32x16& p1, float& mrun, float& lrun, f32x16& o0, f32x16& o1, LAS float* wsf, int kv0, int qpos, int q32, int hi) {
;     ...
;     float rm = fmaxf(p0[0], p1[0]);
; #pragma unroll
;     for (int r = 1; r < 16; ++r) rm = fmaxf(rm, fmaxf(p0[r], p1[r]));
;     rm = fmaxf(rm, xhalf(rm, hi));
;     if (__any(rm > mrun + 8.0f)) {
;         const float mnew = fmaxf(mrun, rm), alpha = ex2(mrun - mnew); mrun = mnew; lrun *= alpha;
;         if (hi == 0) wsf[q32] = alpha;
; template <bool MASK> __device__ __forceinline__ void sm_iter(int var, SmState& st, const bf16x8 (&qr)[6], const LAS unsigned char* kb, const LAS unsigned char* vb, LAS float* wsf, int kv0, int qpos, int q32, int hi) {
;     ...
;     for (int d0 = 0; d0 < ND; ++d0) { kf[2 * d0] = *(const LAS bf16x8*)(kb + d0 * 32); kf[2 * d0 + 1] = *(const LAS bf16x8*)(kb + 32 * KP + d0 * 32); }
;     __builtin_amdgcn_sched_barrier(0);
; #pragma unroll
;     for (int d0 = 0; d0 < ND; ++d0) { p0 = MFMA32(kf[2 * d0], qr[d0], p0); p1 = MFMA32(kf[2 * d0 + 1], qr[d0], p1); }
; #pragma unroll
;     for (int j = 0; j < 4; ++j) { vlo[2 * j] = *(const LAS s16x4*)(vb + j * 32); vhh[2 * j] = *(const LAS s16x4*)(vb + j * 32 + 16);
;         vlo[2 * j + 1] = *(const LAS s16x4*)(vb + 32 * VP + j * 32); vhh[2 * j + 1] = *(const LAS s16x4*)(vb + 32 * VP + j * 32 + 16); }
;     __builtin_amdgcn_sched_barrier(0);
;     if (var != 1) sm_tile<MASK>(p0, p1, st.mrun, st.lrun, st.o0, st.o1, wsf, kv0, qpos, q32, hi);
; #pragma unroll
;     for (int j = 0; j < 4; ++j) {
;         u32x4 pw;
;         if (j < 2) { const int r0 = 8 * (j & 1); pw.x = pk2(p0[r0], p0[r0 + 1]); pw.y = pk2(p0[r0 + 2], p0[r0 + 3]); pw.z = pk2(p0[r0 + 4], p0[r0 + 5]); pw.w = pk2(p0[r0 + 6], p0[r0 + 7]); }
;         else { const int r0 = 8 * (j & 1); pw.x = pk2(p1[r0], p1[r0 + 1]); pw.y = pk2(p1[r0 + 2], p1[r0 + 3]); pw.z = pk2(p1[r0 + 4], p1[r0 + 5]); pw.w = pk2(p1[r0 + 6], p1[r0 + 7]); }
;         const bf16x8 pa = __builtin_bit_cast(bf16x8, pw);
;         { const s16x4 lo = vlo[2 * j], hh = vhh[2 * j]; const bf16x8 vf = {lo[0], lo[1], lo[2], lo[3], hh[0], hh[1], hh[2], hh[3]}; st.o0 = MFMA32(pa, vf, st.o0); }
;         { const s16x4 lo = vlo[2 * j + 1], hh = vhh[2 * j + 1]; const bf16x8 vf = {lo[0], lo[1], lo[2], lo[3], hh[0], hh[1], hh[2], hh[3]}; st.o1 = MFMA32(pa, vf, st.o1); }
;     }
.Lm3_ok2:
	v_exp_f32_e32 v48, v48
	v_exp_f32_e32 v49, v49
	v_exp_f32_e32 v50, v50
	v_add_f32_e32 v15, v48, v49
	v_exp_f32_e32 v51, v51
	v_cvt_pk_bf16_f32 v214, v48, v49
	v_exp_f32_e32 v52, v52
	v_add_f32_e32 v177, v50, v51
	v_exp_f32_e32 v53, v53
	v_cvt_pk_bf16_f32 v215, v50, v51
	v_exp_f32_e32 v54, v54
	v_add_f32_e32 v15, v15, v52
	s_waitcnt lgkmcnt(9)
	v_mfma_f32_32x32x16_bf16 v[64:79], v[116:119], v[84:87], v[198:213]
	v_exp_f32_e32 v55, v55
	v_add_f32_e32 v177, v177, v53
	v_exp_f32_e32 v56, v56
	v_cvt_pk_bf16_f32 v216, v52, v53
	v_exp_f32_e32 v57, v57
	s_waitcnt lgkmcnt(8)
	v_mfma_f32_32x32x16_bf16 v[64:79], v[120:123], v[88:91], v[64:79]
	v_add_f32_e32 v15, v15, v54
	v_exp_f32_e32 v58, v58
	v_add_f32_e32 v177, v177, v55
	v_exp_f32_e32 v59, v59
	v_cvt_pk_bf16_f32 v217, v54, v55
	s_waitcnt lgkmcnt(7)
	v_mfma_f32_32x32x16_bf16 v[64:79], v[124:127], v[92:95], v[64:79]
	v_exp_f32_e32 v60, v60
	v_add_f32_e32 v15, v15, v56
	v_exp_f32_e32 v61, v61
	v_add_f32_e32 v177, v177, v57
	v_exp_f32_e32 v62, v62
	s_waitcnt lgkmcnt(6)
	v_mfma_f32_32x32x16_bf16 v[64:79], v[128:131], v[96:99], v[64:79]
	v_cvt_pk_bf16_f32 v218, v56, v57
	v_exp_f32_e32 v63, v63
	v_add_f32_e32 v15, v15, v58
	v_add_f32_e32 v177, v177, v59
	v_cvt_pk_bf16_f32 v219, v58, v59
	s_waitcnt lgkmcnt(5)
	v_mfma_f32_32x32x16_bf16 v[64:79], v[132:135], v[100:103], v[64:79]
	v_add_f32_e32 v15, v15, v60
	v_add_f32_e32 v177, v177, v61
	v_cvt_pk_bf16_f32 v220, v60, v61
	v_add_f32_e32 v15, v15, v62
	s_waitcnt lgkmcnt(4)
	v_mfma_f32_32x32x16_bf16 v[64:79], v[136:139], v[104:107], v[64:79]
	v_add_f32_e32 v177, v177, v63
	v_cvt_pk_bf16_f32 v221, v62, v63
	v_add_f32_e32 v15, v15, v177
	v_add_f32_e32 v170, v170, v15
	s_waitcnt lgkmcnt(0)
	ds_read_b128 v[116:119], v1 offset:19968
	ds_read_b128 v[120:123], v1 offset:20000
	ds_read_b128 v[124:127], v1 offset:20032
	ds_read_b128 v[128:131], v1 offset:20064
	ds_read_b128 v[132:135], v1 offset:20096
	ds_read_b128 v[136:139], v1 offset:20128
	v_mfma_f32_32x32x16_bf16 v[16:31], v[214:217], v[140:143], v[16:31]
	ds_read2_b64 v[140:143], v14 offset0:16 offset1:18
	v_mfma_f32_32x32x16_bf16 v[32:47], v[214:217], v[144:147], v[32:47]
	ds_read2_b64 v[144:147], v176 offset0:48 offset1:50
	v_mfma_f32_32x32x16_bf16 v[16:31], v[218:221], v[180:183], v[16:31]
	ds_read2_b64 v[180:183], v14 offset0:20 offset1:22
	v_mfma_f32_32x32x16_bf16 v[32:47], v[218:221], v[184:187], v[32:47]
	ds_read2_b64 v[184:187], v176 offset0:52 offset1:54
	v_max3_f32 v15, v64, v65, v66
	v_max3_f32 v177, v67, v68, v69
	v_max3_f32 v15, v15, v70, v71
	v_max3_f32 v177, v177, v72, v73
	v_max3_f32 v15, v15, v74, v75
	v_max3_f32 v177, v177, v76, v77
	v_max3_f32 v15, v15, v78, v79
	v_max_f32_e32 v15, v15, v177
	v_mov_b32_e32 v177, v15
	v_mov_b32_e32 v178, v15
	s_nop 1
	v_permlane32_swap_b32_e32 v177, v178
	v_max3_f32 v15, v15, v177, v178
	v_cmp_gt_f32_e32 vcc, v15, v197
	s_cbranch_vccz .Lm3_ok3
	v_max_f32_e32 v15, v171, v15
	v_sub_f32_e32 v177, v171, v15
	v_exp_f32_e32 v177, v177
	v_sub_f32_e32 v198, v198, v15
	s_and_saveexec_b64 s[20:21], s[40:41]
	ds_write_b32 v149, v177
	s_or_b64 exec, exec, s[20:21]
	v_mul_f32_e32 v170, v170, v177
	v_add_u32_e32 v178, s25, v148
	s_waitcnt lgkmcnt(0)
	ds_read_b128 v[188:191], v178
	ds_read_b128 v[192:195], v178 offset:32
	ds_read_b128 v[222:225], v178 offset:64
	ds_read_b128 v[236:239], v178 offset:96
	v_sub_f32_e32 v64, v64, v15
	v_sub_f32_e32 v65, v65, v15
	v_sub_f32_e32 v66, v66, v15
	v_sub_f32_e32 v67, v67, v15
	v_sub_f32_e32 v68, v68, v15
	v_sub_f32_e32 v69, v69, v15
	v_sub_f32_e32 v70, v70, v15
	v_sub_f32_e32 v71, v71, v15
	v_sub_f32_e32 v72, v72, v15
	v_sub_f32_e32 v73, v73, v15
	v_sub_f32_e32 v74, v74, v15
	v_sub_f32_e32 v75, v75, v15
	v_sub_f32_e32 v76, v76, v15
	v_sub_f32_e32 v77, v77, v15
	v_sub_f32_e32 v78, v78, v15
	v_sub_f32_e32 v79, v79, v15
	v_mov_b32_e32 v199, v198
	v_mov_b32_e32 v200, v198
	v_mov_b32_e32 v201, v198
	v_mov_b32_e32 v202, v198
	v_mov_b32_e32 v203, v198
	v_mov_b32_e32 v204, v198
	v_mov_b32_e32 v205, v198
	v_mov_b32_e32 v206, v198
	v_mov_b32_e32 v207, v198
	v_mov_b32_e32 v208, v198
	v_mov_b32_e32 v209, v198
	v_mov_b32_e32 v210, v198
	v_mov_b32_e32 v211, v198
	v_mov_b32_e32 v212, v198
	v_mov_b32_e32 v213, v198
	v_mov_b32_e32 v171, 0
	v_mov_b32_e32 v197, 0x41000000
	s_nop 11
	s_nop 3
	s_waitcnt lgkmcnt(0)
	v_pk_mul_f32 v[16:17], v[16:17], v[188:189]
	v_pk_mul_f32 v[32:33], v[32:33], v[188:189]
	v_pk_mul_f32 v[18:19], v[18:19], v[190:191]
	v_pk_mul_f32 v[34:35], v[34:35], v[190:191]
	v_pk_mul_f32 v[20:21], v[20:21], v[192:193]
	v_pk_mul_f32 v[36:37], v[36:37], v[192:193]
	v_pk_mul_f32 v[22:23], v[22:23], v[194:195]
	v_pk_mul_f32 v[38:39], v[38:39], v[194:195]
	v_pk_mul_f32 v[24:25], v[24:25], v[222:223]
	v_pk_mul_f32 v[40:41], v[40:41], v[222:223]
	v_pk_mul_f32 v[26:27], v[26:27], v[224:225]
	v_pk_mul_f32 v[42:43], v[42:43], v[224:225]
	v_pk_mul_f32 v[28:29], v[28:29], v[236:237]
	v_pk_mul_f32 v[44:45], v[44:45], v[236:237]
	v_pk_mul_f32 v[30:31], v[30:31], v[238:239]
	v_pk_mul_f32 v[46:47], v[46:47], v[238:239]
; template <bool MASK> __device__ __forceinline__ void sm_tile(f32x16& p0, f32x16& p1, float& mrun, float& lrun, f32x16& o0, f32x16& o1, LAS float* wsf, int kv0, int qpos, int q32, int hi) {
;     ...
;     float rm = fmaxf(p0[0], p1[0]);
; #pragma unroll
;     for (int r = 1; r < 16; ++r) rm = fmaxf(rm, fmaxf(p0[r], p1[r]));
;     rm = fmaxf(rm, xhalf(rm, hi));
;     if (__any(rm > mrun + 8.0f)) {
;         const float mnew = fmaxf(mrun, rm), alpha = ex2(mrun - mnew); mrun = mnew; lrun *= alpha;
;         if (hi == 0) wsf[q32] = alpha;
; template <bool MASK> __device__ __forceinline__ void sm_iter(int var, SmState& st, const bf16x8 (&qr)[6], const LAS unsigned char* kb, const LAS unsigned char* vb, LAS float* wsf, int kv0, int qpos, int q32, int hi) {
;     ...
;     for (int d0 = 0; d0 < ND; ++d0) { kf[2 * d0] = *(const LAS bf16x8*)(kb + d0 * 32); kf[2 * d0 + 1] = *(const LAS bf16x8*)(kb + 32 * KP + d0 * 32); }
;     __builtin_amdgcn_sched_barrier(0);
; #pragma unroll
;     for (int d0 = 0; d0 < ND; ++d0) { p0 = MFMA32(kf[2 * d0], qr[d0], p0); p1 = MFMA32(kf[2 * d0 + 1], qr[d0], p1); }
; #pragma unroll
;     for (int j = 0; j < 4; ++j) { vlo[2 * j] = *(const LAS s16x4*)(vb + j * 32); vhh[2 * j] = *(const LAS s16x4*)(vb + j * 32 + 16);
;         vlo[2 * j + 1] = *(const LAS s16x4*)(vb + 32 * VP + j * 32); vhh[2 * j + 1] = *(const LAS s16x4*)(vb + 32 * VP + j * 32 + 16); }
;     __builtin_amdgcn_sched_barrier(0);
;     if (var != 1) sm_tile<MASK>(p0, p1, st.mrun, st.lrun, st.o0, st.o1, wsf, kv0, qpos, q32, hi);
; #pragma unroll
;     for (int j = 0; j < 4; ++j) {
;         u32x4 pw;
;         if (j < 2) { const int r0 = 8 * (j & 1); pw.x = pk2(p0[r0], p0[r0 + 1]); pw.y = pk2(p0[r0 + 2], p0[r0 + 3]); pw.z = pk2(p0[r0 + 4], p0[r0 + 5]); pw.w = pk2(p0[r0 + 6], p0[r0 + 7]); }
;         else { const int r0 = 8 * (j & 1); pw.x = pk2(p1[r0], p1[r0 + 1]); pw.y = pk2(p1[r0 + 2], p1[r0 + 3]); pw.z = pk2(p1[r0 + 4], p1[r0 + 5]); pw.w = pk2(p1[r0 + 6], p1[r0 + 7]); }
;         const bf16x8 pa = __builtin_bit_cast(bf16x8, pw);
;         { const s16x4 lo = vlo[2 * j], hh = vhh[2 * j]; const bf16x8 vf = {lo[0], lo[1], lo[2], lo[3], hh[0], hh[1], hh[2], hh[3]}; st.o0 = MFMA32(pa, vf, st.o0); }
;         { const s16x4 lo = vlo[2 * j + 1], hh = vhh[2 * j + 1]; const bf16x8 vf = {lo[0], lo[1], lo[2], lo[3], hh[0], hh[1], hh[2], hh[3]}; st.o1 = MFMA32(pa, vf, st.o1); }
;     }
.Lm3_ok3:
	s_xor_b32 s20, s43, 1
	s_mul_i32 s21, s20, 0x6800
	s_add_i32 s21, s21, 0
	s_mulk_i32 s20, 0x4200
	v_add_u32_e32 v226, s21, v150
	s_waitcnt vmcnt(4)
	ds_write_b128 v226, v[6:9]
	s_waitcnt vmcnt(3)
	ds_write_b128 v226, v[2:5] offset:13312
	v_add_u32_e32 v226, s21, v152
	s_waitcnt vmcnt(0)
	ds_write_b128 v226, v[112:115] offset:128
	v_add_u32_e32 v226, s20, v151
	v_add_u32_e32 v227, 0xd000, v226
	v_add_u32_e32 v226, 0xd080, v226
	ds_write2_b64 v227, v[10:11], v[12:13] offset1:1
	ds_write2_b64 v226, v[108:109], v[110:111] offset1:1
	v_exp_f32_e32 v64, v64
	v_exp_f32_e32 v65, v65
	v_exp_f32_e32 v66, v66
	v_add_f32_e32 v15, v64, v65
	v_exp_f32_e32 v67, v67
	v_cvt_pk_bf16_f32 v214, v64, v65
	v_exp_f32_e32 v68, v68
	v_add_f32_e32 v177, v66, v67
	v_exp_f32_e32 v69, v69
	v_cvt_pk_bf16_f32 v215, v66, v67
	v_exp_f32_e32 v70, v70
	v_add_f32_e32 v15, v15, v68
	s_waitcnt lgkmcnt(14)
	v_mfma_f32_32x32x16_bf16 v[48:63], v[116:119], v[84:87], v[198:213]
	v_exp_f32_e32 v71, v71
	v_add_f32_e32 v177, v177, v69
	v_exp_f32_e32 v72, v72
	v_cvt_pk_bf16_f32 v216, v68, v69
	v_exp_f32_e32 v73, v73
	s_waitcnt lgkmcnt(13)
	v_mfma_f32_32x32x16_bf16 v[48:63], v[120:123], v[88:91], v[48:63]
	v_add_f32_e32 v15, v15, v70
	v_exp_f32_e32 v74, v74
	v_add_f32_e32 v177, v177, v71
	v_exp_f32_e32 v75, v75
	v_cvt_pk_bf16_f32 v217, v70, v71
	s_waitcnt lgkmcnt(12)
	v_mfma_f32_32x32x16_bf16 v[48:63], v[124:127], v[92:95], v[48:63]
	v_exp_f32_e32 v76, v76
	v_add_f32_e32 v15, v15, v72
	v_exp_f32_e32 v77, v77
	v_add_f32_e32 v177, v177, v73
	v_exp_f32_e32 v78, v78
	s_waitcnt lgkmcnt(11)
	v_mfma_f32_32x32x16_bf16 v[48:63], v[128:131], v[96:99], v[48:63]
	v_cvt_pk_bf16_f32 v218, v72, v73
	v_exp_f32_e32 v79, v79
	v_add_f32_e32 v15, v15, v74
	v_add_f32_e32 v177, v177, v75
	v_cvt_pk_bf16_f32 v219, v74, v75
	s_waitcnt lgkmcnt(10)
	v_mfma_f32_32x32x16_bf16 v[48:63], v[132:135], v[100:103], v[48:63]
	v_add_f32_e32 v15, v15, v76
	v_add_f32_e32 v177, v177, v77
	v_cvt_pk_bf16_f32 v220, v76, v77
	v_add_f32_e32 v15, v15, v78
	s_waitcnt lgkmcnt(9)
	v_mfma_f32_32x32x16_bf16 v[48:63], v[136:139], v[104:107], v[48:63]
	v_add_f32_e32 v177, v177, v79
	v_cvt_pk_bf16_f32 v221, v78, v79
	v_add_f32_e32 v15, v15, v177
	v_add_f32_e32 v170, v170, v15
	s_waitcnt lgkmcnt(0)
	v_mfma_f32_32x32x16_bf16 v[16:31], v[214:217], v[140:143], v[16:31]
	ds_read2_b64 v[140:143], v14 offset0:24 offset1:26
	v_mfma_f32_32x32x16_bf16 v[32:47], v[214:217], v[144:147], v[32:47]
	ds_read2_b64 v[144:147], v176 offset0:56 offset1:58
	v_mfma_f32_32x32x16_bf16 v[16:31], v[218:221], v[180:183], v[16:31]
	ds_read2_b64 v[180:183], v14 offset0:28 offset1:30
	v_mfma_f32_32x32x16_bf16 v[32:47], v[218:221], v[184:187], v[32:47]
	ds_read2_b64 v[184:187], v176 offset0:60 offset1:62
	s_nop 3
	v_max3_f32 v15, v48, v49, v50
	v_max3_f32 v177, v51, v52, v53
	v_max3_f32 v15, v15, v54, v55
	v_max3_f32 v177, v177, v56, v57
	v_max3_f32 v15, v15, v58, v59
	v_max3_f32 v177, v177, v60, v61
	v_max3_f32 v15, v15, v62, v63
	v_max_f32_e32 v15, v15, v177
	v_mov_b32_e32 v177, v15
	v_mov_b32_e32 v178, v15
	s_nop 1
	v_permlane32_swap_b32_e32 v177, v178
	v_max3_f32 v15, v15, v177, v178
	v_cmp_gt_f32_e32 vcc, v15, v197
	s_cbranch_vccz .Lm3_ok4
	v_max_f32_e32 v15, v171, v15
	v_sub_f32_e32 v177, v171, v15
	v_exp_f32_e32 v177, v177
	v_sub_f32_e32 v198, v198, v15
	s_and_saveexec_b64 s[20:21], s[40:41]
	ds_write_b32 v149, v177
	s_or_b64 exec, exec, s[20:21]
	v_mul_f32_e32 v170, v170, v177
	v_add_u32_e32 v178, s25, v148
	s_waitcnt lgkmcnt(0)
	ds_read_b128 v[188:191], v178
	ds_read_b128 v[192:195], v178 offset:32
	ds_read_b128 v[222:225], v178 offset:64
	ds_read_b128 v[236:239], v178 offset:96
	v_sub_f32_e32 v48, v48, v15
	v_sub_f32_e32 v49, v49, v15
	v_sub_f32_e32 v50, v50, v15
	v_sub_f32_e32 v51, v51, v15
	v_sub_f32_e32 v52, v52, v15
	v_sub_f32_e32 v53, v53, v15
	v_sub_f32_e32 v54, v54, v15
	v_sub_f32_e32 v55, v55, v15
	v_sub_f32_e32 v56, v56, v15
	v_sub_f32_e32 v57, v57, v15
	v_sub_f32_e32 v58, v58, v15
	v_sub_f32_e32 v59, v59, v15
	v_sub_f32_e32 v60, v60, v15
	v_sub_f32_e32 v61, v61, v15
	v_sub_f32_e32 v62, v62, v15
	v_sub_f32_e32 v63, v63, v15
	v_mov_b32_e32 v199, v198
	v_mov_b32_e32 v200, v198
	v_mov_b32_e32 v201, v198
	v_mov_b32_e32 v202, v198
	v_mov_b32_e32 v203, v198
	v_mov_b32_e32 v204, v198
	v_mov_b32_e32 v205, v198
	v_mov_b32_e32 v206, v198
	v_mov_b32_e32 v207, v198
	v_mov_b32_e32 v208, v198
	v_mov_b32_e32 v209, v198
	v_mov_b32_e32 v210, v198
	v_mov_b32_e32 v211, v198
	v_mov_b32_e32 v212, v198
	v_mov_b32_e32 v213, v198
	v_mov_b32_e32 v171, 0
	v_mov_b32_e32 v197, 0x41000000
	s_nop 11
	s_nop 3
	s_waitcnt lgkmcnt(0)
	v_pk_mul_f32 v[16:17], v[16:17], v[188:189]
	v_pk_mul_f32 v[32:33], v[32:33], v[188:189]
	v_pk_mul_f32 v[18:19], v[18:19], v[190:191]
	v_pk_mul_f32 v[34:35], v[34:35], v[190:191]
	v_pk_mul_f32 v[20:21], v[20:21], v[192:193]
	v_pk_mul_f32 v[36:37], v[36:37], v[192:193]
	v_pk_mul_f32 v[22:23], v[22:23], v[194:195]
	v_pk_mul_f32 v[38:39], v[38:39], v[194:195]
	v_pk_mul_f32 v[24:25], v[24:25], v[222:223]
	v_pk_mul_f32 v[40:41], v[40:41], v[222:223]
	v_pk_mul_f32 v[26:27], v[26:27], v[224:225]
	v_pk_mul_f32 v[42:43], v[42:43], v[224:225]
	v_pk_mul_f32 v[28:29], v[28:29], v[236:237]
	v_pk_mul_f32 v[44:45], v[44:45], v[236:237]
	v_pk_mul_f32 v[30:31], v[30:31], v[238:239]
	v_pk_mul_f32 v[46:47], v[46:47], v[238:239]
